# MLP2 visits row blocks newest-first (row-block index xor 24 within each XCD chunk) so HID tiles are read while still in the memory-side cache; final LN sweep order follows
# baseline (speedup 1.0000x reference)
.LBB0_25:
	s_ashr_i32 s2, s26, 3
	s_add_i32 s2, s34, s2
	s_ashr_i32 s3, s2, 31
	s_lshr_b32 s3, s3, 22
	s_add_i32 s3, s2, s3
	s_and_b32 s3, s3, 0xfc00
	s_sub_i32 s2, s2, s3
	s_sext_i32_i16 s3, s2
	s_bfe_u32 s3, s3, 0x5001a
	s_add_i32 s3, s2, s3
	s_sext_i32_i16 s26, s3
	s_and_b32 s3, s3, 0xffe0
	s_sub_i32 s2, s2, s3
	s_bfe_i32 s3, s2, 0x80000
	s_bfe_u32 s3, s3, 0x3000c
	s_add_i32 s3, s2, s3
	s_bfe_i32 s27, s3, 0x80000
	s_and_b32 s3, s3, 0xf8
	s_ashr_i32 s26, s26, 5
	s_sub_i32 s2, s2, s3
	s_lshl_b32 s26, s26, 3
	s_sext_i32_i16 s27, s27
	s_sext_i32_i8 s2, s2
	s_add_i32 s52, s26, s2
	s_xor_b32 s52, s52, 24
	s_ashr_i32 s40, s27, 3

.LBB0_39:
	s_ashr_i32 s20, s42, 3
	s_add_i32 s20, s44, s20
	s_ashr_i32 s21, s20, 31
	s_lshr_b32 s21, s21, 22
	s_add_i32 s21, s20, s21
	s_and_b32 s21, s21, 0xfc00
	s_sub_i32 s20, s20, s21
	s_sext_i32_i16 s21, s20
	s_bfe_u32 s21, s21, 0x5001a
	s_add_i32 s21, s20, s21
	s_sext_i32_i16 s42, s21
	s_and_b32 s21, s21, 0xffe0
	s_sub_i32 s20, s20, s21
	s_bfe_i32 s21, s20, 0x80000
	s_bfe_u32 s21, s21, 0x3000c
	s_add_i32 s21, s20, s21
	s_bfe_i32 s43, s21, 0x80000
	s_and_b32 s21, s21, 0xf8
	s_ashr_i32 s42, s42, 5
	s_sub_i32 s20, s20, s21
	s_lshl_b32 s42, s42, 3
	s_sext_i32_i16 s43, s43
	s_sext_i32_i8 s20, s20
	s_add_i32 s60, s42, s20
	s_xor_b32 s60, s60, 24
	s_ashr_i32 s62, s43, 3

.LBB0_75:
	s_ashr_i32 s2, s22, 3
	s_add_i32 s2, s26, s2
	s_ashr_i32 s3, s2, 31
	s_lshr_b32 s3, s3, 22
	s_add_i32 s3, s2, s3
	s_and_b32 s3, s3, 0xfc00
	s_sub_i32 s2, s2, s3
	s_sext_i32_i16 s3, s2
	s_bfe_u32 s3, s3, 0x5001a
	s_add_i32 s3, s2, s3
	s_sext_i32_i16 s22, s3
	s_and_b32 s3, s3, 0xffe0
	s_sub_i32 s2, s2, s3
	s_bfe_i32 s3, s2, 0x80000
	s_bfe_u32 s3, s3, 0x3000c
	s_add_i32 s3, s2, s3
	s_bfe_i32 s23, s3, 0x80000
	s_and_b32 s3, s3, 0xf8
	s_ashr_i32 s22, s22, 5
	s_sub_i32 s2, s2, s3
	s_lshl_b32 s22, s22, 3
	s_sext_i32_i16 s23, s23
	s_sext_i32_i8 s2, s2
	s_add_i32 s52, s22, s2
	s_xor_b32 s52, s52, 24
	s_ashr_i32 s40, s23, 3

.LBB0_87:
	s_ashr_i32 s20, s22, 3
	s_add_i32 s20, s34, s20
	s_ashr_i32 s21, s20, 31
	s_lshr_b32 s21, s21, 22
	s_add_i32 s21, s20, s21
	s_and_b32 s21, s21, 0xfc00
	s_sub_i32 s20, s20, s21
	s_sext_i32_i16 s21, s20
	s_bfe_u32 s21, s21, 0x5001a
	s_add_i32 s21, s20, s21
	s_sext_i32_i16 s22, s21
	s_and_b32 s21, s21, 0xffe0
	s_sub_i32 s20, s20, s21
	s_bfe_i32 s21, s20, 0x80000
	s_bfe_u32 s21, s21, 0x3000c
	s_add_i32 s21, s20, s21
	s_bfe_i32 s23, s21, 0x80000
	s_and_b32 s21, s21, 0xf8
	s_ashr_i32 s22, s22, 5
	s_sub_i32 s20, s20, s21
	s_lshl_b32 s22, s22, 3
	s_sext_i32_i16 s23, s23
	s_sext_i32_i8 s20, s20
	s_add_i32 s60, s22, s20
	s_xor_b32 s60, s60, 24
	s_ashr_i32 s62, s23, 3

.LBB0_835:
	v_mov_b32_e32 v58, 0
	v_mov_b32_e32 v59, 0
	s_cmp_lg_u32 s20, 0x800
	s_cbranch_scc1 .Lfl_noperm
	v_lshrrev_b32_e32 v58, 11, v32
	v_and_b32_e32 v59, 3, v58
	v_lshrrev_b32_e32 v60, 2, v58
	v_lshl_or_b32 v59, v59, 2, v60
	v_sub_u32_e32 v58, v59, v58
	v_ashrrev_i32_e32 v59, 31, v58
	v_lshlrev_b64 v[58:59], 23, v[58:59]
